# LayerNorm (k5 loop only): gamma/beta hoisted out of the row loop
# baseline (speedup 1.0000x reference)
.LBB0_141:
	s_andn2_b64 vcc, exec, s[28:29]
	s_cbranch_vccnz .LBB0_228
	s_cmp_gt_i32 s25, 4
	s_mov_b64 s[0:1], -1
	s_cbranch_scc0 .LBB0_152
	v_mov_b32_e32 v0, v169
	s_waitcnt vmcnt(7)
	v_mov_b32_e32 v2, v169
	v_readlane_b32 s0, v254, 32
	s_nop 1
	v_add_u32_e32 v2, s0, v2
	s_mov_b32 s0, 0x200000
	v_cmp_gt_u32_e32 vcc, s0, v2
	s_and_saveexec_b64 s[28:29], vcc
	s_cbranch_execz .LBB0_151
	s_load_dword s0, s[22:23], 0x0
	v_lshrrev_b32_e32 v44, 6, v2
	v_and_b32_e32 v2, 63, v0
	v_readlane_b32 s44, v253, 18
	v_lshlrev_b32_e32 v0, 4, v2
	v_readlane_b32 s58, v253, 32
	v_readlane_b32 s59, v253, 33
	s_waitcnt lgkmcnt(0)
	s_lshl_b32 s42, s0, 2
	v_readlane_b32 s0, v254, 28
	v_lshl_add_u64 v[34:35], s[58:59], 0, v[0:1]
	v_lshl_add_u64 v[36:37], s[34:35], 0, v[0:1]
	v_lshl_add_u64 v[38:39], s[40:41], 0, v[0:1]
	v_lshlrev_b32_e32 v0, 3, v2
	v_readlane_b32 s1, v254, 29
	v_cmp_eq_u32_e32 vcc, 0, v2
	s_ashr_i32 s43, s42, 31
	v_lshl_add_u64 v[40:41], s[0:1], 0, v[0:1]
	v_cmp_lt_i32_e64 s[0:1], v184, v183
	s_mov_b64 s[34:35], 0
	v_readlane_b32 s45, v253, 19
	v_cndmask_b32_e64 v0, v182, v184, s[0:1]
	v_cmp_lt_i32_e64 s[0:1], v185, v183
	v_lshlrev_b32_e32 v50, 2, v0
	v_readlane_b32 s46, v253, 20
	v_cndmask_b32_e64 v0, v182, v185, s[0:1]
	v_lshlrev_b32_e32 v51, 2, v0
	v_xor_b32_e32 v0, 8, v182
	v_cmp_lt_i32_e64 s[0:1], v0, v183
	v_readlane_b32 s47, v253, 21
	v_readlane_b32 s48, v253, 22
	v_cndmask_b32_e64 v0, v182, v0, s[0:1]
	v_lshlrev_b32_e32 v52, 2, v0
	v_xor_b32_e32 v0, 4, v182
	v_cmp_lt_i32_e64 s[0:1], v0, v183
	v_readlane_b32 s49, v253, 23
	v_readlane_b32 s50, v253, 24
	v_cndmask_b32_e64 v0, v182, v0, s[0:1]
	v_lshlrev_b32_e32 v53, 2, v0
	v_xor_b32_e32 v0, 2, v182
	v_cmp_lt_i32_e64 s[0:1], v0, v183
	v_readlane_b32 s51, v253, 25
	v_readlane_b32 s52, v253, 26
	v_cndmask_b32_e64 v0, v182, v0, s[0:1]
	v_lshlrev_b32_e32 v54, 2, v0
	v_xor_b32_e32 v0, 1, v182
	v_cmp_lt_i32_e64 s[0:1], v0, v183
	v_readlane_b32 s53, v253, 27
	v_readlane_b32 s54, v253, 28
	v_cndmask_b32_e64 v0, v182, v0, s[0:1]
	v_lshlrev_b32_e32 v55, 2, v0
	v_readlane_b32 s55, v253, 29
	v_readlane_b32 s56, v253, 30
	v_readlane_b32 s57, v253, 31
	global_load_dwordx4 v[100:103], v[36:37], off
	global_load_dwordx4 v[116:119], v[38:39], off
	global_load_dwordx4 v[104:107], v[36:37], off offset:1024
	global_load_dwordx4 v[120:123], v[38:39], off offset:1024
	global_load_dwordx4 v[108:111], v[36:37], off offset:2048
	global_load_dwordx4 v[124:127], v[38:39], off offset:2048
	global_load_dwordx4 v[112:115], v[36:37], off offset:3072
	global_load_dwordx4 v[128:131], v[38:39], off offset:3072
	s_waitcnt vmcnt(0)
	s_branch .LBB0_146

.LBB0_149:
	s_or_b64 exec, exec, s[0:1]
	v_pk_mul_f32 v[32:33], v[32:33], v[0:1] op_sel_hi:[1,0]
	v_pk_mul_f32 v[30:31], v[30:31], v[0:1] op_sel_hi:[1,0]
	v_lshlrev_b64 v[44:45], 10, v[44:45]
	v_lshl_add_u64 v[44:45], v[44:45], 1, v[40:41]
	v_pk_mul_f32 v[28:29], v[28:29], v[0:1] op_sel_hi:[1,0]
	v_pk_mul_f32 v[26:27], v[26:27], v[0:1] op_sel_hi:[1,0]
	v_pk_mul_f32 v[24:25], v[24:25], v[0:1] op_sel_hi:[1,0]
	v_pk_mul_f32 v[22:23], v[22:23], v[0:1] op_sel_hi:[1,0]
	v_pk_mul_f32 v[20:21], v[20:21], v[0:1] op_sel_hi:[1,0]
	v_pk_mul_f32 v[18:19], v[18:19], v[0:1] op_sel_hi:[1,0]
	v_pk_fma_f32 v[32:33], v[32:33], v[102:103], v[118:119]
	v_pk_fma_f32 v[30:31], v[30:31], v[100:101], v[116:117]
	s_nop 0
	v_cvt_pk_bf16_f32 v30, v30, v31
	v_cvt_pk_bf16_f32 v31, v32, v33
	global_store_dwordx2 v[44:45], v[30:31], off
	v_pk_fma_f32 v[28:29], v[28:29], v[106:107], v[122:123]
	v_pk_fma_f32 v[26:27], v[26:27], v[104:105], v[120:121]
	s_nop 0
	v_cvt_pk_bf16_f32 v26, v26, v27
	v_cvt_pk_bf16_f32 v27, v28, v29
	global_store_dwordx2 v[44:45], v[26:27], off offset:512
	v_pk_fma_f32 v[24:25], v[24:25], v[110:111], v[126:127]
	v_pk_fma_f32 v[22:23], v[22:23], v[108:109], v[124:125]
	s_nop 0
	v_cvt_pk_bf16_f32 v22, v22, v23
	v_cvt_pk_bf16_f32 v23, v24, v25
	global_store_dwordx2 v[44:45], v[22:23], off offset:1024
	v_pk_fma_f32 v[20:21], v[20:21], v[114:115], v[130:131]
	v_pk_fma_f32 v[18:19], v[18:19], v[112:113], v[128:129]
	s_nop 0
	v_cvt_pk_bf16_f32 v18, v18, v19
	v_cvt_pk_bf16_f32 v19, v20, v21
	global_store_dwordx2 v[44:45], v[18:19], off offset:1536
	s_and_saveexec_b64 s[0:1], s[38:39]
	s_cbranch_execz .LBB0_145
	v_mov_b32_e32 v0, v47
	v_pk_mul_f32 v[16:17], v[16:17], v[0:1] op_sel_hi:[1,0]
	v_pk_mul_f32 v[14:15], v[14:15], v[0:1] op_sel_hi:[1,0]
	v_ashrrev_i32_e32 v43, 31, v42
	v_pk_mul_f32 v[12:13], v[12:13], v[0:1] op_sel_hi:[1,0]
	v_pk_mul_f32 v[10:11], v[10:11], v[0:1] op_sel_hi:[1,0]
	v_pk_mul_f32 v[8:9], v[8:9], v[0:1] op_sel_hi:[1,0]
	v_pk_mul_f32 v[6:7], v[6:7], v[0:1] op_sel_hi:[1,0]
	v_pk_mul_f32 v[4:5], v[4:5], v[0:1] op_sel_hi:[1,0]
	v_pk_mul_f32 v[2:3], v[2:3], v[0:1] op_sel_hi:[1,0]
	v_pk_fma_f32 v[16:17], v[16:17], v[102:103], v[118:119]
	v_pk_fma_f32 v[14:15], v[14:15], v[100:101], v[116:117]
	s_nop 0
	v_cvt_pk_bf16_f32 v14, v14, v15
	v_cvt_pk_bf16_f32 v15, v16, v17
	v_lshlrev_b64 v[16:17], 11, v[42:43]
	v_lshl_add_u64 v[22:23], v[40:41], 0, v[16:17]
	global_store_dwordx2 v[22:23], v[14:15], off
	v_pk_fma_f32 v[12:13], v[12:13], v[106:107], v[122:123]
	v_pk_fma_f32 v[10:11], v[10:11], v[104:105], v[120:121]
	s_nop 0
	v_cvt_pk_bf16_f32 v10, v10, v11
	v_cvt_pk_bf16_f32 v11, v12, v13
	global_store_dwordx2 v[22:23], v[10:11], off offset:512
	v_pk_fma_f32 v[8:9], v[8:9], v[110:111], v[126:127]
	v_pk_fma_f32 v[6:7], v[6:7], v[108:109], v[124:125]
	s_nop 0
	v_cvt_pk_bf16_f32 v6, v6, v7
	v_cvt_pk_bf16_f32 v7, v8, v9
	global_store_dwordx2 v[22:23], v[6:7], off offset:1024
	v_pk_fma_f32 v[4:5], v[4:5], v[114:115], v[130:131]
	v_pk_fma_f32 v[2:3], v[2:3], v[112:113], v[128:129]
	s_nop 0
	v_cvt_pk_bf16_f32 v2, v2, v3
	v_cvt_pk_bf16_f32 v3, v4, v5
	global_store_dwordx2 v[22:23], v[2:3], off offset:1536
	s_branch .LBB0_145
